# out-proj EpiRes epilogue rewritten by hand: base-row loads issued two rows ahead into spare fragment VGPRs with counted vmcnt waits (no per-row store drain), saddr addressing
# baseline (speedup 1.0000x reference)
; __device__ __forceinline__ unsigned pk2(float lo, float hi) { const f32x2_t v = {lo, hi}; const bf16v2_t b = __builtin_convertvector(v, bf16v2_t); return __builtin_bit_cast(unsigned, b); }
;     __device__ __forceinline__ void operator()(const f32x4 (&acc)[2][2][4][2], const pg8::Unit& u, int wr, int wc, int fr, int fq) const {
;         const int row0 = u.pm * 256 + wr * 64 + fr, col0 = u.pn * 256 + wc * 32 + 4 * fq;
;         f32x4 g00 = {0.f, 0.f, 0.f, 0.f}, g01 = g00, g10 = g00, g11 = g00;
;         if (XG) { g00 = *(const f32x4*)(gain + col0); g01 = *(const f32x4*)(gain + col0 + 16); g10 = *(const f32x4*)(gain + col0 + 128); g11 = *(const f32x4*)(gain + col0 + 144); }
; #pragma unroll
;         for (int ai = 0; ai < 2; ++ai)
; #pragma unroll
;             for (int m = 0; m < 4; ++m) { const int row = row0 + ai * 128 + m * 16; const size_t off = (size_t)row * DM + col0;
;                 const f32x4 b00 = *(const f32x4*)(base + off), b01 = *(const f32x4*)(base + off + 16), b10 = *(const f32x4*)(base + off + 128), b11 = *(const f32x4*)(base + off + 144);
;                 const f32x4 o00 = b00 + acc[ai][0][m][0], o01 = b01 + acc[ai][0][m][1], o10 = b10 + acc[ai][1][m][0], o11 = b11 + acc[ai][1][m][1];
;                 *(f32x4*)(out + off) = o00; *(f32x4*)(out + off + 16) = o01; *(f32x4*)(out + off + 128) = o10; *(f32x4*)(out + off + 144) = o11;
;                 if (XG) {
;                     const f32x4 x00 = o00 * g00, x01 = o01 * g01, x10 = o10 * g10, x11 = o11 * g11; u32x2 w;
;                     w.x = pk2(x00[0], x00[1]); w.y = pk2(x00[2], x00[3]); *(u32x2*)(XG + off) = w;
;                     w.x = pk2(x01[0], x01[1]); w.y = pk2(x01[2], x01[3]); *(u32x2*)(XG + off + 16) = w;
;                     w.x = pk2(x10[0], x10[1]); w.y = pk2(x10[2], x10[3]); *(u32x2*)(XG + off + 128) = w;
;                     w.x = pk2(x11[0], x11[1]); w.y = pk2(x11[2], x11[3]); *(u32x2*)(XG + off + 144) = w;
;                     const f32x4 q = o00 * o00 + o01 * o01 + o10 * o10 + o11 * o11;
;                     float ss = (q[0] + q[1]) + (q[2] + q[3]);
;                     ss += __shfl_xor(ss, 16); ss += __shfl_xor(ss, 32);
;                     if (fq == 0) SS[(size_t)row * 16 + u.pn * 4 + wc] = ss;
;                 }
;                 asm volatile("" ::: "memory"); }
.LBB0_885:
	v_lshl_add_u32 v154, s40, 8, v156
	v_lshl_or_b32 v152, s38, 8, v158
	s_lshl_b32 s38, s38, 2
	s_ashr_i32 s39, s38, 31
	s_lshl_b32 s26, s76, 2
	s_lshl_b32 s98, s38, 2
	s_add_i32 s98, s98, s26
	v_lshlrev_b32_e32 v204, 2, v152
	v_lshl_add_u32 v176, v154, 12, v204
	global_load_dwordx4 v[94:97], v204, s[14:15]
	global_load_dwordx4 v[90:93], v204, s[14:15] offset:64
	global_load_dwordx4 v[86:89], v204, s[14:15] offset:512
	global_load_dwordx4 v[82:85], v204, s[14:15] offset:576
	global_load_dwordx4 v[160:163], v176, s[12:13]
	global_load_dwordx4 v[164:167], v176, s[12:13] offset:64
	global_load_dwordx4 v[168:171], v176, s[12:13] offset:512
	global_load_dwordx4 v[172:175], v176, s[12:13] offset:576
	v_add_u32_e32 v208, 0x10000, v176
	global_load_dwordx4 v[188:191], v208, s[12:13]
	global_load_dwordx4 v[192:195], v208, s[12:13] offset:64
	global_load_dwordx4 v[196:199], v208, s[12:13] offset:512
	global_load_dwordx4 v[200:203], v208, s[12:13] offset:576
	v_lshl_add_u32 v183, v154, 6, s98
	v_xor_b32_e32 v184, 16, v244
	v_xor_b32_e32 v185, 32, v244
	v_lshlrev_b32_e32 v184, 2, v184
	v_lshlrev_b32_e32 v185, 2, v185
	s_waitcnt vmcnt(4)
	v_pk_add_f32 v[142:143], v[142:143], v[160:161]
	v_pk_add_f32 v[144:145], v[144:145], v[162:163]
	v_pk_add_f32 v[138:139], v[138:139], v[164:165]
	v_pk_add_f32 v[140:141], v[140:141], v[166:167]
	v_pk_add_f32 v[134:135], v[134:135], v[168:169]
	v_pk_add_f32 v[136:137], v[136:137], v[170:171]
	v_pk_add_f32 v[130:131], v[130:131], v[172:173]
	v_pk_add_f32 v[132:133], v[132:133], v[174:175]
	v_add_u32_e32 v208, 0x20000, v176
	global_load_dwordx4 v[160:163], v208, s[12:13]
	global_load_dwordx4 v[164:167], v208, s[12:13] offset:64
	global_load_dwordx4 v[168:171], v208, s[12:13] offset:512
	global_load_dwordx4 v[172:175], v208, s[12:13] offset:576
	v_mov_b32_e32 v177, v176
	global_store_dwordx4 v177, v[142:145], s[8:9]
	global_store_dwordx4 v177, v[138:141], s[8:9] offset:64
	global_store_dwordx4 v177, v[134:137], s[8:9] offset:512
	global_store_dwordx4 v177, v[130:133], s[8:9] offset:576
	v_lshrrev_b32_e32 v182, 1, v177
	v_pk_mul_f32 v[208:209], v[94:95], v[142:143]
	v_pk_mul_f32 v[210:211], v[96:97], v[144:145]
	v_pk_mul_f32 v[204:205], v[138:139], v[138:139]
	v_pk_mul_f32 v[206:207], v[140:141], v[140:141]
	v_cvt_pk_bf16_f32 v152, v208, v209
	v_cvt_pk_bf16_f32 v153, v210, v211
	global_store_dwordx2 v182, v[152:153], s[16:17]
	v_pk_mul_f32 v[208:209], v[90:91], v[138:139]
	v_pk_mul_f32 v[210:211], v[92:93], v[140:141]
	v_pk_fma_f32 v[204:205], v[142:143], v[142:143], v[204:205]
	v_pk_fma_f32 v[206:207], v[144:145], v[144:145], v[206:207]
	v_cvt_pk_bf16_f32 v154, v208, v209
	v_cvt_pk_bf16_f32 v155, v210, v211
	global_store_dwordx2 v182, v[154:155], s[16:17] offset:32
	v_pk_mul_f32 v[208:209], v[86:87], v[134:135]
	v_pk_mul_f32 v[210:211], v[88:89], v[136:137]
	v_pk_fma_f32 v[204:205], v[134:135], v[134:135], v[204:205]
	v_pk_fma_f32 v[206:207], v[136:137], v[136:137], v[206:207]
	v_cvt_pk_bf16_f32 v152, v208, v209
	v_cvt_pk_bf16_f32 v153, v210, v211
	global_store_dwordx2 v182, v[152:153], s[16:17] offset:256
	v_pk_mul_f32 v[208:209], v[82:83], v[130:131]
	v_pk_mul_f32 v[210:211], v[84:85], v[132:133]
	v_pk_fma_f32 v[204:205], v[130:131], v[130:131], v[204:205]
	v_pk_fma_f32 v[206:207], v[132:133], v[132:133], v[206:207]
	v_cvt_pk_bf16_f32 v154, v208, v209
	v_cvt_pk_bf16_f32 v155, v210, v211
	global_store_dwordx2 v182, v[154:155], s[16:17] offset:288
	v_add_f32_e32 v204, v204, v205
	v_add_f32_e32 v205, v206, v207
	v_add_f32_e32 v204, v204, v205
	ds_bpermute_b32 v205, v184, v204
	v_mov_b32_e32 v206, v183
	s_waitcnt lgkmcnt(0)
	v_add_f32_e32 v204, v204, v205
	ds_bpermute_b32 v205, v185, v204
	s_waitcnt lgkmcnt(0)
	v_add_f32_e32 v204, v204, v205
	s_and_saveexec_b64 s[40:41], s[2:3]
	global_store_dword v206, v204, s[10:11]
	s_mov_b64 exec, s[40:41]
	s_waitcnt vmcnt(12)
	v_pk_add_f32 v[126:127], v[126:127], v[188:189]
	v_pk_add_f32 v[128:129], v[128:129], v[190:191]
	v_pk_add_f32 v[122:123], v[122:123], v[192:193]
	v_pk_add_f32 v[124:125], v[124:125], v[194:195]
	v_pk_add_f32 v[118:119], v[118:119], v[196:197]
	v_pk_add_f32 v[120:121], v[120:121], v[198:199]
	v_pk_add_f32 v[114:115], v[114:115], v[200:201]
	v_pk_add_f32 v[116:117], v[116:117], v[202:203]
	v_add_u32_e32 v208, 0x30000, v176
	global_load_dwordx4 v[188:191], v208, s[12:13]
	global_load_dwordx4 v[192:195], v208, s[12:13] offset:64
	global_load_dwordx4 v[196:199], v208, s[12:13] offset:512
	global_load_dwordx4 v[200:203], v208, s[12:13] offset:576
	v_add_u32_e32 v177, 0x10000, v176
	global_store_dwordx4 v177, v[126:129], s[8:9]
	global_store_dwordx4 v177, v[122:125], s[8:9] offset:64
	global_store_dwordx4 v177, v[118:121], s[8:9] offset:512
	global_store_dwordx4 v177, v[114:117], s[8:9] offset:576
	v_lshrrev_b32_e32 v182, 1, v177
	v_pk_mul_f32 v[208:209], v[94:95], v[126:127]
	v_pk_mul_f32 v[210:211], v[96:97], v[128:129]
	v_pk_mul_f32 v[204:205], v[122:123], v[122:123]
	v_pk_mul_f32 v[206:207], v[124:125], v[124:125]
	v_cvt_pk_bf16_f32 v152, v208, v209
	v_cvt_pk_bf16_f32 v153, v210, v211
	global_store_dwordx2 v182, v[152:153], s[16:17]
	v_pk_mul_f32 v[208:209], v[90:91], v[122:123]
	v_pk_mul_f32 v[210:211], v[92:93], v[124:125]
	v_pk_fma_f32 v[204:205], v[126:127], v[126:127], v[204:205]
	v_pk_fma_f32 v[206:207], v[128:129], v[128:129], v[206:207]
	v_cvt_pk_bf16_f32 v154, v208, v209
	v_cvt_pk_bf16_f32 v155, v210, v211
	global_store_dwordx2 v182, v[154:155], s[16:17] offset:32
	v_pk_mul_f32 v[208:209], v[86:87], v[118:119]
	v_pk_mul_f32 v[210:211], v[88:89], v[120:121]
	v_pk_fma_f32 v[204:205], v[118:119], v[118:119], v[204:205]
	v_pk_fma_f32 v[206:207], v[120:121], v[120:121], v[206:207]
	v_cvt_pk_bf16_f32 v152, v208, v209
	v_cvt_pk_bf16_f32 v153, v210, v211
	global_store_dwordx2 v182, v[152:153], s[16:17] offset:256
	v_pk_mul_f32 v[208:209], v[82:83], v[114:115]
	v_pk_mul_f32 v[210:211], v[84:85], v[116:117]
	v_pk_fma_f32 v[204:205], v[114:115], v[114:115], v[204:205]
	v_pk_fma_f32 v[206:207], v[116:117], v[116:117], v[206:207]
	v_cvt_pk_bf16_f32 v154, v208, v209
	v_cvt_pk_bf16_f32 v155, v210, v211
	global_store_dwordx2 v182, v[154:155], s[16:17] offset:288
	v_add_f32_e32 v204, v204, v205
	v_add_f32_e32 v205, v206, v207
	v_add_f32_e32 v204, v204, v205
	ds_bpermute_b32 v205, v184, v204
	v_add_u32_e32 v206, 0x400, v183
	s_waitcnt lgkmcnt(0)
; __device__ __forceinline__ unsigned pk2(float lo, float hi) { const f32x2_t v = {lo, hi}; const bf16v2_t b = __builtin_convertvector(v, bf16v2_t); return __builtin_bit_cast(unsigned, b); }
;     __device__ __forceinline__ void operator()(const f32x4 (&acc)[2][2][4][2], const pg8::Unit& u, int wr, int wc, int fr, int fq) const {
;     ...
;             for (int m = 0; m < 4; ++m) { const int row = row0 + ai * 128 + m * 16; const size_t off = (size_t)row * DM + col0;
;                 const f32x4 b00 = *(const f32x4*)(base + off), b01 = *(const f32x4*)(base + off + 16), b10 = *(const f32x4*)(base + off + 128), b11 = *(const f32x4*)(base + off + 144);
;                 const f32x4 o00 = b00 + acc[ai][0][m][0], o01 = b01 + acc[ai][0][m][1], o10 = b10 + acc[ai][1][m][0], o11 = b11 + acc[ai][1][m][1];
;                 *(f32x4*)(out + off) = o00; *(f32x4*)(out + off + 16) = o01; *(f32x4*)(out + off + 128) = o10; *(f32x4*)(out + off + 144) = o11;
;                 if (XG) {
;                     const f32x4 x00 = o00 * g00, x01 = o01 * g01, x10 = o10 * g10, x11 = o11 * g11; u32x2 w;
;                     w.x = pk2(x00[0], x00[1]); w.y = pk2(x00[2], x00[3]); *(u32x2*)(XG + off) = w;
;                     w.x = pk2(x01[0], x01[1]); w.y = pk2(x01[2], x01[3]); *(u32x2*)(XG + off + 16) = w;
;                     w.x = pk2(x10[0], x10[1]); w.y = pk2(x10[2], x10[3]); *(u32x2*)(XG + off + 128) = w;
;                     w.x = pk2(x11[0], x11[1]); w.y = pk2(x11[2], x11[3]); *(u32x2*)(XG + off + 144) = w;
;                     const f32x4 q = o00 * o00 + o01 * o01 + o10 * o10 + o11 * o11;
;                     float ss = (q[0] + q[1]) + (q[2] + q[3]);
;                     ss += __shfl_xor(ss, 16); ss += __shfl_xor(ss, 32);
;                     if (fq == 0) SS[(size_t)row * 16 + u.pn * 4 + wc] = ss;
;                 }
;                 asm volatile("" ::: "memory"); }
	v_add_f32_e32 v204, v204, v205
	ds_bpermute_b32 v205, v185, v204
	s_waitcnt lgkmcnt(0)
	v_add_f32_e32 v204, v204, v205
	s_and_saveexec_b64 s[40:41], s[2:3]
	global_store_dword v206, v204, s[10:11]
	s_mov_b64 exec, s[40:41]
	s_waitcnt vmcnt(20)
	v_pk_add_f32 v[110:111], v[110:111], v[160:161]
	v_pk_add_f32 v[112:113], v[112:113], v[162:163]
	v_pk_add_f32 v[106:107], v[106:107], v[164:165]
	v_pk_add_f32 v[108:109], v[108:109], v[166:167]
	v_pk_add_f32 v[102:103], v[102:103], v[168:169]
	v_pk_add_f32 v[104:105], v[104:105], v[170:171]
	v_pk_add_f32 v[98:99], v[98:99], v[172:173]
	v_pk_add_f32 v[100:101], v[100:101], v[174:175]
	v_add_u32_e32 v208, 0x80000, v176
	global_load_dwordx4 v[160:163], v208, s[12:13]
	global_load_dwordx4 v[164:167], v208, s[12:13] offset:64
	global_load_dwordx4 v[168:171], v208, s[12:13] offset:512
	global_load_dwordx4 v[172:175], v208, s[12:13] offset:576
	v_add_u32_e32 v177, 0x20000, v176
	global_store_dwordx4 v177, v[110:113], s[8:9]
	global_store_dwordx4 v177, v[106:109], s[8:9] offset:64
	global_store_dwordx4 v177, v[102:105], s[8:9] offset:512
	global_store_dwordx4 v177, v[98:101], s[8:9] offset:576
	v_lshrrev_b32_e32 v182, 1, v177
	v_pk_mul_f32 v[208:209], v[94:95], v[110:111]
	v_pk_mul_f32 v[210:211], v[96:97], v[112:113]
	v_pk_mul_f32 v[204:205], v[106:107], v[106:107]
	v_pk_mul_f32 v[206:207], v[108:109], v[108:109]
	v_cvt_pk_bf16_f32 v152, v208, v209
	v_cvt_pk_bf16_f32 v153, v210, v211
	global_store_dwordx2 v182, v[152:153], s[16:17]
	v_pk_mul_f32 v[208:209], v[90:91], v[106:107]
	v_pk_mul_f32 v[210:211], v[92:93], v[108:109]
	v_pk_fma_f32 v[204:205], v[110:111], v[110:111], v[204:205]
	v_pk_fma_f32 v[206:207], v[112:113], v[112:113], v[206:207]
	v_cvt_pk_bf16_f32 v154, v208, v209
	v_cvt_pk_bf16_f32 v155, v210, v211
	global_store_dwordx2 v182, v[154:155], s[16:17] offset:32
	v_pk_mul_f32 v[208:209], v[86:87], v[102:103]
	v_pk_mul_f32 v[210:211], v[88:89], v[104:105]
	v_pk_fma_f32 v[204:205], v[102:103], v[102:103], v[204:205]
	v_pk_fma_f32 v[206:207], v[104:105], v[104:105], v[206:207]
	v_cvt_pk_bf16_f32 v152, v208, v209
	v_cvt_pk_bf16_f32 v153, v210, v211
	global_store_dwordx2 v182, v[152:153], s[16:17] offset:256
	v_pk_mul_f32 v[208:209], v[82:83], v[98:99]
	v_pk_mul_f32 v[210:211], v[84:85], v[100:101]
	v_pk_fma_f32 v[204:205], v[98:99], v[98:99], v[204:205]
	v_pk_fma_f32 v[206:207], v[100:101], v[100:101], v[206:207]
	v_cvt_pk_bf16_f32 v154, v208, v209
	v_cvt_pk_bf16_f32 v155, v210, v211
	global_store_dwordx2 v182, v[154:155], s[16:17] offset:288
	v_add_f32_e32 v204, v204, v205
	v_add_f32_e32 v205, v206, v207
	v_add_f32_e32 v204, v204, v205
	ds_bpermute_b32 v205, v184, v204
	v_add_u32_e32 v206, 0x800, v183
	s_waitcnt lgkmcnt(0)
	v_add_f32_e32 v204, v204, v205
	ds_bpermute_b32 v205, v185, v204
	s_waitcnt lgkmcnt(0)
	v_add_f32_e32 v204, v204, v205
	s_and_saveexec_b64 s[40:41], s[2:3]
	global_store_dword v206, v204, s[10:11]
	s_mov_b64 exec, s[40:41]
	s_waitcnt vmcnt(20)
	v_pk_add_f32 v[78:79], v[78:79], v[188:189]
	v_pk_add_f32 v[80:81], v[80:81], v[190:191]
	v_pk_add_f32 v[74:75], v[74:75], v[192:193]
	v_pk_add_f32 v[76:77], v[76:77], v[194:195]
	v_pk_add_f32 v[70:71], v[70:71], v[196:197]
	v_pk_add_f32 v[72:73], v[72:73], v[198:199]
	v_pk_add_f32 v[66:67], v[66:67], v[200:201]
	v_pk_add_f32 v[68:69], v[68:69], v[202:203]
	v_add_u32_e32 v208, 0x90000, v176
	global_load_dwordx4 v[188:191], v208, s[12:13]
	global_load_dwordx4 v[192:195], v208, s[12:13] offset:64
	global_load_dwordx4 v[196:199], v208, s[12:13] offset:512
	global_load_dwordx4 v[200:203], v208, s[12:13] offset:576
	v_add_u32_e32 v177, 0x30000, v176
	global_store_dwordx4 v177, v[78:81], s[8:9]
	global_store_dwordx4 v177, v[74:77], s[8:9] offset:64
	global_store_dwordx4 v177, v[70:73], s[8:9] offset:512
	global_store_dwordx4 v177, v[66:69], s[8:9] offset:576
	v_lshrrev_b32_e32 v182, 1, v177
	v_pk_mul_f32 v[208:209], v[94:95], v[78:79]
	v_pk_mul_f32 v[210:211], v[96:97], v[80:81]
	v_pk_mul_f32 v[204:205], v[74:75], v[74:75]
	v_pk_mul_f32 v[206:207], v[76:77], v[76:77]
	v_cvt_pk_bf16_f32 v152, v208, v209
	v_cvt_pk_bf16_f32 v153, v210, v211
	global_store_dwordx2 v182, v[152:153], s[16:17]
	v_pk_mul_f32 v[208:209], v[90:91], v[74:75]
	v_pk_mul_f32 v[210:211], v[92:93], v[76:77]
	v_pk_fma_f32 v[204:205], v[78:79], v[78:79], v[204:205]
	v_pk_fma_f32 v[206:207], v[80:81], v[80:81], v[206:207]
	v_cvt_pk_bf16_f32 v154, v208, v209
	v_cvt_pk_bf16_f32 v155, v210, v211
	global_store_dwordx2 v182, v[154:155], s[16:17] offset:32
	v_pk_mul_f32 v[208:209], v[86:87], v[70:71]
	v_pk_mul_f32 v[210:211], v[88:89], v[72:73]
	v_pk_fma_f32 v[204:205], v[70:71], v[70:71], v[204:205]
	v_pk_fma_f32 v[206:207], v[72:73], v[72:73], v[206:207]
	v_cvt_pk_bf16_f32 v152, v208, v209
	v_cvt_pk_bf16_f32 v153, v210, v211
	global_store_dwordx2 v182, v[152:153], s[16:17] offset:256
	v_pk_mul_f32 v[208:209], v[82:83], v[66:67]
	v_pk_mul_f32 v[210:211], v[84:85], v[68:69]
	v_pk_fma_f32 v[204:205], v[66:67], v[66:67], v[204:205]
	v_pk_fma_f32 v[206:207], v[68:69], v[68:69], v[206:207]
	v_cvt_pk_bf16_f32 v154, v208, v209
	v_cvt_pk_bf16_f32 v155, v210, v211
	global_store_dwordx2 v182, v[154:155], s[16:17] offset:288
	v_add_f32_e32 v204, v204, v205
	v_add_f32_e32 v205, v206, v207
	v_add_f32_e32 v204, v204, v205
	ds_bpermute_b32 v205, v184, v204
	v_add_u32_e32 v206, 0xc00, v183
	s_waitcnt lgkmcnt(0)
	v_add_f32_e32 v204, v204, v205
	ds_bpermute_b32 v205, v185, v204
	s_waitcnt lgkmcnt(0)
	v_add_f32_e32 v204, v204, v205
	s_and_saveexec_b64 s[40:41], s[2:3]
	global_store_dword v206, v204, s[10:11]
	s_mov_b64 exec, s[40:41]
	s_waitcnt vmcnt(20)
; __device__ __forceinline__ unsigned pk2(float lo, float hi) { const f32x2_t v = {lo, hi}; const bf16v2_t b = __builtin_convertvector(v, bf16v2_t); return __builtin_bit_cast(unsigned, b); }
;     __device__ __forceinline__ void operator()(const f32x4 (&acc)[2][2][4][2], const pg8::Unit& u, int wr, int wc, int fr, int fq) const {
;     ...
;             for (int m = 0; m < 4; ++m) { const int row = row0 + ai * 128 + m * 16; const size_t off = (size_t)row * DM + col0;
;                 const f32x4 b00 = *(const f32x4*)(base + off), b01 = *(const f32x4*)(base + off + 16), b10 = *(const f32x4*)(base + off + 128), b11 = *(const f32x4*)(base + off + 144);
;                 const f32x4 o00 = b00 + acc[ai][0][m][0], o01 = b01 + acc[ai][0][m][1], o10 = b10 + acc[ai][1][m][0], o11 = b11 + acc[ai][1][m][1];
;                 *(f32x4*)(out + off) = o00; *(f32x4*)(out + off + 16) = o01; *(f32x4*)(out + off + 128) = o10; *(f32x4*)(out + off + 144) = o11;
;                 if (XG) {
;                     const f32x4 x00 = o00 * g00, x01 = o01 * g01, x10 = o10 * g10, x11 = o11 * g11; u32x2 w;
;                     w.x = pk2(x00[0], x00[1]); w.y = pk2(x00[2], x00[3]); *(u32x2*)(XG + off) = w;
;                     w.x = pk2(x01[0], x01[1]); w.y = pk2(x01[2], x01[3]); *(u32x2*)(XG + off + 16) = w;
;                     w.x = pk2(x10[0], x10[1]); w.y = pk2(x10[2], x10[3]); *(u32x2*)(XG + off + 128) = w;
;                     w.x = pk2(x11[0], x11[1]); w.y = pk2(x11[2], x11[3]); *(u32x2*)(XG + off + 144) = w;
;                     const f32x4 q = o00 * o00 + o01 * o01 + o10 * o10 + o11 * o11;
;                     float ss = (q[0] + q[1]) + (q[2] + q[3]);
;                     ss += __shfl_xor(ss, 16); ss += __shfl_xor(ss, 32);
;                     if (fq == 0) SS[(size_t)row * 16 + u.pn * 4 + wc] = ss;
;                 }
;                 asm volatile("" ::: "memory"); }
	v_pk_add_f32 v[62:63], v[62:63], v[160:161]
	v_pk_add_f32 v[64:65], v[64:65], v[162:163]
	v_pk_add_f32 v[58:59], v[58:59], v[164:165]
	v_pk_add_f32 v[60:61], v[60:61], v[166:167]
	v_pk_add_f32 v[54:55], v[54:55], v[168:169]
	v_pk_add_f32 v[56:57], v[56:57], v[170:171]
	v_pk_add_f32 v[50:51], v[50:51], v[172:173]
	v_pk_add_f32 v[52:53], v[52:53], v[174:175]
	v_add_u32_e32 v208, 0xa0000, v176
	global_load_dwordx4 v[160:163], v208, s[12:13]
	global_load_dwordx4 v[164:167], v208, s[12:13] offset:64
	global_load_dwordx4 v[168:171], v208, s[12:13] offset:512
	global_load_dwordx4 v[172:175], v208, s[12:13] offset:576
	v_add_u32_e32 v177, 0x80000, v176
	global_store_dwordx4 v177, v[62:65], s[8:9]
	global_store_dwordx4 v177, v[58:61], s[8:9] offset:64
	global_store_dwordx4 v177, v[54:57], s[8:9] offset:512
	global_store_dwordx4 v177, v[50:53], s[8:9] offset:576
	v_lshrrev_b32_e32 v182, 1, v177
	v_pk_mul_f32 v[208:209], v[94:95], v[62:63]
	v_pk_mul_f32 v[210:211], v[96:97], v[64:65]
	v_pk_mul_f32 v[204:205], v[58:59], v[58:59]
	v_pk_mul_f32 v[206:207], v[60:61], v[60:61]
	v_cvt_pk_bf16_f32 v152, v208, v209
	v_cvt_pk_bf16_f32 v153, v210, v211
	global_store_dwordx2 v182, v[152:153], s[16:17]
	v_pk_mul_f32 v[208:209], v[90:91], v[58:59]
	v_pk_mul_f32 v[210:211], v[92:93], v[60:61]
	v_pk_fma_f32 v[204:205], v[62:63], v[62:63], v[204:205]
	v_pk_fma_f32 v[206:207], v[64:65], v[64:65], v[206:207]
	v_cvt_pk_bf16_f32 v154, v208, v209
	v_cvt_pk_bf16_f32 v155, v210, v211
	global_store_dwordx2 v182, v[154:155], s[16:17] offset:32
	v_pk_mul_f32 v[208:209], v[86:87], v[54:55]
	v_pk_mul_f32 v[210:211], v[88:89], v[56:57]
	v_pk_fma_f32 v[204:205], v[54:55], v[54:55], v[204:205]
	v_pk_fma_f32 v[206:207], v[56:57], v[56:57], v[206:207]
	v_cvt_pk_bf16_f32 v152, v208, v209
	v_cvt_pk_bf16_f32 v153, v210, v211
	global_store_dwordx2 v182, v[152:153], s[16:17] offset:256
	v_pk_mul_f32 v[208:209], v[82:83], v[50:51]
	v_pk_mul_f32 v[210:211], v[84:85], v[52:53]
	v_pk_fma_f32 v[204:205], v[50:51], v[50:51], v[204:205]
	v_pk_fma_f32 v[206:207], v[52:53], v[52:53], v[206:207]
	v_cvt_pk_bf16_f32 v154, v208, v209
	v_cvt_pk_bf16_f32 v155, v210, v211
	global_store_dwordx2 v182, v[154:155], s[16:17] offset:288
	v_add_f32_e32 v204, v204, v205
	v_add_f32_e32 v205, v206, v207
	v_add_f32_e32 v204, v204, v205
	ds_bpermute_b32 v205, v184, v204
	v_add_u32_e32 v206, 0x2000, v183
	s_waitcnt lgkmcnt(0)
	v_add_f32_e32 v204, v204, v205
	ds_bpermute_b32 v205, v185, v204
	s_waitcnt lgkmcnt(0)
	v_add_f32_e32 v204, v204, v205
	s_and_saveexec_b64 s[40:41], s[2:3]
	global_store_dword v206, v204, s[10:11]
	s_mov_b64 exec, s[40:41]
	s_waitcnt vmcnt(20)
	v_pk_add_f32 v[46:47], v[46:47], v[188:189]
	v_pk_add_f32 v[48:49], v[48:49], v[190:191]
	v_pk_add_f32 v[42:43], v[42:43], v[192:193]
	v_pk_add_f32 v[44:45], v[44:45], v[194:195]
	v_pk_add_f32 v[38:39], v[38:39], v[196:197]
	v_pk_add_f32 v[40:41], v[40:41], v[198:199]
	v_pk_add_f32 v[34:35], v[34:35], v[200:201]
	v_pk_add_f32 v[36:37], v[36:37], v[202:203]
	v_add_u32_e32 v208, 0xb0000, v176
	global_load_dwordx4 v[188:191], v208, s[12:13]
	global_load_dwordx4 v[192:195], v208, s[12:13] offset:64
	global_load_dwordx4 v[196:199], v208, s[12:13] offset:512
	global_load_dwordx4 v[200:203], v208, s[12:13] offset:576
	v_add_u32_e32 v177, 0x90000, v176
	global_store_dwordx4 v177, v[46:49], s[8:9]
	global_store_dwordx4 v177, v[42:45], s[8:9] offset:64
	global_store_dwordx4 v177, v[38:41], s[8:9] offset:512
	global_store_dwordx4 v177, v[34:37], s[8:9] offset:576
	v_lshrrev_b32_e32 v182, 1, v177
	v_pk_mul_f32 v[208:209], v[94:95], v[46:47]
	v_pk_mul_f32 v[210:211], v[96:97], v[48:49]
	v_pk_mul_f32 v[204:205], v[42:43], v[42:43]
	v_pk_mul_f32 v[206:207], v[44:45], v[44:45]
	v_cvt_pk_bf16_f32 v152, v208, v209
	v_cvt_pk_bf16_f32 v153, v210, v211
	global_store_dwordx2 v182, v[152:153], s[16:17]
	v_pk_mul_f32 v[208:209], v[90:91], v[42:43]
	v_pk_mul_f32 v[210:211], v[92:93], v[44:45]
	v_pk_fma_f32 v[204:205], v[46:47], v[46:47], v[204:205]
	v_pk_fma_f32 v[206:207], v[48:49], v[48:49], v[206:207]
	v_cvt_pk_bf16_f32 v154, v208, v209
	v_cvt_pk_bf16_f32 v155, v210, v211
	global_store_dwordx2 v182, v[154:155], s[16:17] offset:32
	v_pk_mul_f32 v[208:209], v[86:87], v[38:39]
	v_pk_mul_f32 v[210:211], v[88:89], v[40:41]
	v_pk_fma_f32 v[204:205], v[38:39], v[38:39], v[204:205]
	v_pk_fma_f32 v[206:207], v[40:41], v[40:41], v[206:207]
	v_cvt_pk_bf16_f32 v152, v208, v209
	v_cvt_pk_bf16_f32 v153, v210, v211
	global_store_dwordx2 v182, v[152:153], s[16:17] offset:256
	v_pk_mul_f32 v[208:209], v[82:83], v[34:35]
	v_pk_mul_f32 v[210:211], v[84:85], v[36:37]
	v_pk_fma_f32 v[204:205], v[34:35], v[34:35], v[204:205]
	v_pk_fma_f32 v[206:207], v[36:37], v[36:37], v[206:207]
	v_cvt_pk_bf16_f32 v154, v208, v209
	v_cvt_pk_bf16_f32 v155, v210, v211
	global_store_dwordx2 v182, v[154:155], s[16:17] offset:288
	v_add_f32_e32 v204, v204, v205
	v_add_f32_e32 v205, v206, v207
	v_add_f32_e32 v204, v204, v205
	ds_bpermute_b32 v205, v184, v204
	v_add_u32_e32 v206, 0x2400, v183
	s_waitcnt lgkmcnt(0)
; __device__ __forceinline__ unsigned pk2(float lo, float hi) { const f32x2_t v = {lo, hi}; const bf16v2_t b = __builtin_convertvector(v, bf16v2_t); return __builtin_bit_cast(unsigned, b); }
;     __device__ __forceinline__ void operator()(const f32x4 (&acc)[2][2][4][2], const pg8::Unit& u, int wr, int wc, int fr, int fq) const {
;     ...
;             for (int m = 0; m < 4; ++m) { const int row = row0 + ai * 128 + m * 16; const size_t off = (size_t)row * DM + col0;
;                 const f32x4 b00 = *(const f32x4*)(base + off), b01 = *(const f32x4*)(base + off + 16), b10 = *(const f32x4*)(base + off + 128), b11 = *(const f32x4*)(base + off + 144);
;                 const f32x4 o00 = b00 + acc[ai][0][m][0], o01 = b01 + acc[ai][0][m][1], o10 = b10 + acc[ai][1][m][0], o11 = b11 + acc[ai][1][m][1];
;                 *(f32x4*)(out + off) = o00; *(f32x4*)(out + off + 16) = o01; *(f32x4*)(out + off + 128) = o10; *(f32x4*)(out + off + 144) = o11;
;                 if (XG) {
;                     const f32x4 x00 = o00 * g00, x01 = o01 * g01, x10 = o10 * g10, x11 = o11 * g11; u32x2 w;
;                     w.x = pk2(x00[0], x00[1]); w.y = pk2(x00[2], x00[3]); *(u32x2*)(XG + off) = w;
;                     w.x = pk2(x01[0], x01[1]); w.y = pk2(x01[2], x01[3]); *(u32x2*)(XG + off + 16) = w;
;                     w.x = pk2(x10[0], x10[1]); w.y = pk2(x10[2], x10[3]); *(u32x2*)(XG + off + 128) = w;
;                     w.x = pk2(x11[0], x11[1]); w.y = pk2(x11[2], x11[3]); *(u32x2*)(XG + off + 144) = w;
;                     const f32x4 q = o00 * o00 + o01 * o01 + o10 * o10 + o11 * o11;
;                     float ss = (q[0] + q[1]) + (q[2] + q[3]);
;                     ss += __shfl_xor(ss, 16); ss += __shfl_xor(ss, 32);
;                     if (fq == 0) SS[(size_t)row * 16 + u.pn * 4 + wc] = ss;
;                 }
;                 asm volatile("" ::: "memory"); }
	v_add_f32_e32 v204, v204, v205
	ds_bpermute_b32 v205, v185, v204
	s_waitcnt lgkmcnt(0)
	v_add_f32_e32 v204, v204, v205
	s_and_saveexec_b64 s[40:41], s[2:3]
	global_store_dword v206, v204, s[10:11]
	s_mov_b64 exec, s[40:41]
	s_waitcnt vmcnt(20)
	v_pk_add_f32 v[30:31], v[30:31], v[160:161]
	v_pk_add_f32 v[32:33], v[32:33], v[162:163]
	v_pk_add_f32 v[26:27], v[26:27], v[164:165]
	v_pk_add_f32 v[28:29], v[28:29], v[166:167]
	v_pk_add_f32 v[22:23], v[22:23], v[168:169]
	v_pk_add_f32 v[24:25], v[24:25], v[170:171]
	v_pk_add_f32 v[18:19], v[18:19], v[172:173]
	v_pk_add_f32 v[20:21], v[20:21], v[174:175]
	v_add_u32_e32 v177, 0xa0000, v176
	global_store_dwordx4 v177, v[30:33], s[8:9]
	global_store_dwordx4 v177, v[26:29], s[8:9] offset:64
	global_store_dwordx4 v177, v[22:25], s[8:9] offset:512
	global_store_dwordx4 v177, v[18:21], s[8:9] offset:576
	v_lshrrev_b32_e32 v182, 1, v177
	v_pk_mul_f32 v[208:209], v[94:95], v[30:31]
	v_pk_mul_f32 v[210:211], v[96:97], v[32:33]
	v_pk_mul_f32 v[204:205], v[26:27], v[26:27]
	v_pk_mul_f32 v[206:207], v[28:29], v[28:29]
	v_cvt_pk_bf16_f32 v152, v208, v209
	v_cvt_pk_bf16_f32 v153, v210, v211
	global_store_dwordx2 v182, v[152:153], s[16:17]
	v_pk_mul_f32 v[208:209], v[90:91], v[26:27]
	v_pk_mul_f32 v[210:211], v[92:93], v[28:29]
	v_pk_fma_f32 v[204:205], v[30:31], v[30:31], v[204:205]
	v_pk_fma_f32 v[206:207], v[32:33], v[32:33], v[206:207]
	v_cvt_pk_bf16_f32 v154, v208, v209
	v_cvt_pk_bf16_f32 v155, v210, v211
	global_store_dwordx2 v182, v[154:155], s[16:17] offset:32
	v_pk_mul_f32 v[208:209], v[86:87], v[22:23]
	v_pk_mul_f32 v[210:211], v[88:89], v[24:25]
	v_pk_fma_f32 v[204:205], v[22:23], v[22:23], v[204:205]
	v_pk_fma_f32 v[206:207], v[24:25], v[24:25], v[206:207]
	v_cvt_pk_bf16_f32 v152, v208, v209
	v_cvt_pk_bf16_f32 v153, v210, v211
	global_store_dwordx2 v182, v[152:153], s[16:17] offset:256
	v_pk_mul_f32 v[208:209], v[82:83], v[18:19]
	v_pk_mul_f32 v[210:211], v[84:85], v[20:21]
	v_pk_fma_f32 v[204:205], v[18:19], v[18:19], v[204:205]
	v_pk_fma_f32 v[206:207], v[20:21], v[20:21], v[206:207]
	v_cvt_pk_bf16_f32 v154, v208, v209
	v_cvt_pk_bf16_f32 v155, v210, v211
	global_store_dwordx2 v182, v[154:155], s[16:17] offset:288
	v_add_f32_e32 v204, v204, v205
	v_add_f32_e32 v205, v206, v207
	v_add_f32_e32 v204, v204, v205
	ds_bpermute_b32 v205, v184, v204
	v_add_u32_e32 v206, 0x2800, v183
	s_waitcnt lgkmcnt(0)
	v_add_f32_e32 v204, v204, v205
	ds_bpermute_b32 v205, v185, v204
	s_waitcnt lgkmcnt(0)
	v_add_f32_e32 v204, v204, v205
	s_and_saveexec_b64 s[40:41], s[2:3]
	global_store_dword v206, v204, s[10:11]
	s_mov_b64 exec, s[40:41]
	s_waitcnt vmcnt(16)
	v_pk_add_f32 v[14:15], v[14:15], v[188:189]
	v_pk_add_f32 v[16:17], v[16:17], v[190:191]
	v_pk_add_f32 v[10:11], v[10:11], v[192:193]
	v_pk_add_f32 v[12:13], v[12:13], v[194:195]
	v_pk_add_f32 v[6:7], v[6:7], v[196:197]
	v_pk_add_f32 v[8:9], v[8:9], v[198:199]
	v_pk_add_f32 v[2:3], v[2:3], v[200:201]
	v_pk_add_f32 v[4:5], v[4:5], v[202:203]
	v_add_u32_e32 v177, 0xb0000, v176
	global_store_dwordx4 v177, v[14:17], s[8:9]
	global_store_dwordx4 v177, v[10:13], s[8:9] offset:64
	global_store_dwordx4 v177, v[6:9], s[8:9] offset:512
	global_store_dwordx4 v177, v[2:5], s[8:9] offset:576
	v_lshrrev_b32_e32 v182, 1, v177
	v_pk_mul_f32 v[208:209], v[94:95], v[14:15]
	v_pk_mul_f32 v[210:211], v[96:97], v[16:17]
	v_pk_mul_f32 v[204:205], v[10:11], v[10:11]
	v_pk_mul_f32 v[206:207], v[12:13], v[12:13]
	v_cvt_pk_bf16_f32 v152, v208, v209
	v_cvt_pk_bf16_f32 v153, v210, v211
	global_store_dwordx2 v182, v[152:153], s[16:17]
	v_pk_mul_f32 v[208:209], v[90:91], v[10:11]
	v_pk_mul_f32 v[210:211], v[92:93], v[12:13]
	v_pk_fma_f32 v[204:205], v[14:15], v[14:15], v[204:205]
	v_pk_fma_f32 v[206:207], v[16:17], v[16:17], v[206:207]
	v_cvt_pk_bf16_f32 v154, v208, v209
	v_cvt_pk_bf16_f32 v155, v210, v211
	global_store_dwordx2 v182, v[154:155], s[16:17] offset:32
	v_pk_mul_f32 v[208:209], v[86:87], v[6:7]
	v_pk_mul_f32 v[210:211], v[88:89], v[8:9]
	v_pk_fma_f32 v[204:205], v[6:7], v[6:7], v[204:205]
	v_pk_fma_f32 v[206:207], v[8:9], v[8:9], v[206:207]
	v_cvt_pk_bf16_f32 v152, v208, v209
	v_cvt_pk_bf16_f32 v153, v210, v211
	global_store_dwordx2 v182, v[152:153], s[16:17] offset:256
	v_pk_mul_f32 v[208:209], v[82:83], v[2:3]
	v_pk_mul_f32 v[210:211], v[84:85], v[4:5]
	v_pk_fma_f32 v[204:205], v[2:3], v[2:3], v[204:205]
	v_pk_fma_f32 v[206:207], v[4:5], v[4:5], v[206:207]
	v_cvt_pk_bf16_f32 v154, v208, v209
	v_cvt_pk_bf16_f32 v155, v210, v211
	global_store_dwordx2 v182, v[154:155], s[16:17] offset:288
	v_add_f32_e32 v204, v204, v205
	v_add_f32_e32 v205, v206, v207
	v_add_f32_e32 v204, v204, v205
	ds_bpermute_b32 v205, v184, v204
	v_add_u32_e32 v206, 0x2c00, v183
	s_waitcnt lgkmcnt(0)
	v_add_f32_e32 v204, v204, v205
	ds_bpermute_b32 v205, v185, v204
	s_waitcnt lgkmcnt(0)
	v_add_f32_e32 v204, v204, v205
	s_and_saveexec_b64 s[40:41], s[2:3]
	global_store_dword v206, v204, s[10:11]
	s_mov_b64 exec, s[40:41]
